# v17 plus odd WGs enter the V^T GEMM phase 8us late
# speedup vs baseline: 1.0019x; 1.0019x over previous
;     __device__ void init(int M, int N, int G_, int c_, unsigned long long mask_ = 0ull) { nM = M / BM; nN = mask_ ? __builtin_popcountll(mask_) : N / BM; nwg = nM * nN; G = G_; c = c_; mask = mask_; }
; #define LAUNDER() do { tid = threadIdx.x; asm volatile("" : "+v"(tid)); lane = tid & 63; wid = __builtin_amdgcn_readfirstlane(tid >> 6); bx = blockIdx.x; asm volatile("" : "+s"(bx)); \
;         vcu = (G % 8 == 0) ? (bx % 8) * (G / 8) + bx / 8 : bx; gw = vcu * 8 + wid; ws = P.ws; asm volatile("" : "+s"(ws)); Q.ws = ws; XB = (bf16_t*)(ws + WS_XB); } while (0)
; __global__ void __launch_bounds__(512, 2) trunk_fwd(Params P) {
;     ...
;         LAUNDER();
;         if (PH(2)) {   pg8::Gemm g{(const bf16_t*)(ws + WS_WIN) + (size_t)2048 * DM, XB, AW, T, DM}; pg8::StaticOrder S; S.init(AW, T, G, bx);
;             Epi<EPI_PLAIN> E{}; E.O = (bf16_t*)(ws + WS_VT); E.ldc = T;
;             pg8::gemm_phase(lds, g, S, E); }
.LBB0_225:
	s_or_b64 exec, exec, s[2:3]
	s_xor_b64 s[0:1], s[50:51], -1
	v_writelane_b32 v254, s0, 59
	s_waitcnt lgkmcnt(0)
	v_mov_b32_e32 v0, v160
	s_mov_b64 s[6:7], s[44:45]
	v_writelane_b32 v254, s1, 60
	s_xor_b64 s[0:1], s[96:97], -1
	v_writelane_b32 v254, s0, 61
	v_mov_b32_e32 v8, v160
	s_nop 0
	v_writelane_b32 v254, s1, 62
	v_readlane_b32 s0, v252, 50
	s_barrier
	s_bitcmp1_b32 s0, 0
	s_cbranch_scc0 .Lstagger_p2_done
	s_sleep 127
	s_sleep 127
.Lstagger_p2_done:
	s_cmpk_gt_i32 s0, 0x1ff
	v_readfirstlane_b32 s14, v8
	s_cbranch_scc1 .LBB0_249
	s_ashr_i32 s1, s0, 31
	s_lshr_b32 s2, s1, 29
	s_add_i32 s8, s0, s2
	s_and_b32 s2, s8, -8
	s_sub_i32 s4, s0, s2
	s_cmp_gt_i32 s4, -1
	s_mov_b64 s[2:3], -1
	s_cbranch_scc0 .LBB0_228
	s_lshl_b32 s10, s4, 6
	s_mov_b64 s[2:3], 0
